# attention row sums into two interleaved running accumulators (consecutive adds independent)
# speedup vs baseline: 1.0017x; 1.0017x over previous
.LBB0_1480:
	v_readfirstlane_b32 s44, v203
	v_readfirstlane_b32 s45, v205
	s_mov_b64 s[40:41], s[94:95]
	s_mov_b64 s[42:43], s[94:95]
	s_movk_i32 s46, 0x41
	s_add_u32 s45, s45, 0x2000
	v_mul_f32_e32 v189, 0.5, v189
	v_mov_b32_e32 v183, 0

.Latt_cont_a:
	v_exp_f32_e32 v112, v112
	v_exp_f32_e32 v113, v113
	v_exp_f32_e32 v114, v114
	v_exp_f32_e32 v115, v115
	v_exp_f32_e32 v116, v116
	v_exp_f32_e32 v117, v117
	v_exp_f32_e32 v118, v118
	v_exp_f32_e32 v119, v119
	v_add_f32_e32 v189, v189, v112
	v_add_f32_e32 v183, v183, v113
	v_add_f32_e32 v189, v189, v114
	v_add_f32_e32 v183, v183, v115
	v_add_f32_e32 v189, v189, v116
	v_add_f32_e32 v183, v183, v117
	v_add_f32_e32 v189, v189, v118
	v_add_f32_e32 v183, v183, v119
	v_cvt_pk_bf16_f32 v112, v112, v113
	v_cvt_pk_bf16_f32 v113, v114, v115
	v_cvt_pk_bf16_f32 v114, v116, v117
	v_cvt_pk_bf16_f32 v115, v118, v119
	v_exp_f32_e32 v120, v120
	v_exp_f32_e32 v121, v121
	s_waitcnt lgkmcnt(8)
	v_mfma_f32_32x32x16_bf16 v[48:63], v[232:235], v[112:115], v[48:63]
	v_exp_f32_e32 v122, v122
	v_exp_f32_e32 v123, v123
	v_exp_f32_e32 v124, v124
	v_mfma_f32_32x32x16_bf16 v[32:47], v[236:239], v[112:115], v[32:47]
	v_exp_f32_e32 v125, v125
	v_exp_f32_e32 v126, v126
	v_exp_f32_e32 v127, v127
	v_mfma_f32_32x32x16_bf16 v[16:31], v[240:243], v[112:115], v[16:31]
	v_add_f32_e32 v189, v189, v120
	v_add_f32_e32 v183, v183, v121
	v_add_f32_e32 v189, v189, v122
	v_add_f32_e32 v183, v183, v123
	v_add_f32_e32 v189, v189, v124
	v_add_f32_e32 v183, v183, v125
	v_mfma_f32_32x32x16_bf16 v[0:15], v[244:247], v[112:115], v[0:15]
	ds_read_b128 v[232:235], v167 offset:32768
	ds_read_b128 v[236:239], v167 offset:36864
	ds_read_b128 v[240:243], v167 offset:40960
	ds_read_b128 v[244:247], v167 offset:45056
	v_add_f32_e32 v189, v189, v126
	v_add_f32_e32 v183, v183, v127
	v_cvt_pk_bf16_f32 v116, v120, v121
	v_cvt_pk_bf16_f32 v117, v122, v123
	v_cvt_pk_bf16_f32 v118, v124, v125
	v_cvt_pk_bf16_f32 v119, v126, v127
	s_nop 0
	s_waitcnt lgkmcnt(8)
	v_mfma_f32_32x32x16_bf16 v[48:63], v[64:67], v[116:119], v[48:63]
	v_exp_f32_e32 v80, v80
	v_exp_f32_e32 v81, v81
	v_exp_f32_e32 v82, v82
	v_mfma_f32_32x32x16_bf16 v[32:47], v[68:71], v[116:119], v[32:47]
	v_exp_f32_e32 v83, v83
	v_exp_f32_e32 v84, v84
	v_exp_f32_e32 v85, v85
	v_mfma_f32_32x32x16_bf16 v[16:31], v[72:75], v[116:119], v[16:31]
	v_exp_f32_e32 v86, v86
	v_exp_f32_e32 v87, v87
	v_add_f32_e32 v189, v189, v80
	v_add_f32_e32 v183, v183, v81
	v_mfma_f32_32x32x16_bf16 v[0:15], v[76:79], v[116:119], v[0:15]
	v_add_f32_e32 v189, v189, v82
	v_add_f32_e32 v183, v183, v83
	v_add_f32_e32 v189, v189, v84
	v_add_f32_e32 v183, v183, v85
	v_add_f32_e32 v189, v189, v86
	v_add_f32_e32 v183, v183, v87
	v_cvt_pk_bf16_f32 v80, v80, v81
	v_cvt_pk_bf16_f32 v81, v82, v83
	v_cvt_pk_bf16_f32 v82, v84, v85
	v_cvt_pk_bf16_f32 v83, v86, v87
	s_nop 0
	s_waitcnt lgkmcnt(4)
	v_mfma_f32_32x32x16_bf16 v[48:63], v[216:219], v[80:83], v[48:63]
	v_exp_f32_e32 v88, v88
	v_exp_f32_e32 v89, v89
	v_exp_f32_e32 v90, v90
	v_mfma_f32_32x32x16_bf16 v[32:47], v[220:223], v[80:83], v[32:47]
	v_exp_f32_e32 v91, v91
	v_exp_f32_e32 v92, v92
	v_exp_f32_e32 v93, v93
	v_mfma_f32_32x32x16_bf16 v[16:31], v[224:227], v[80:83], v[16:31]
	v_exp_f32_e32 v94, v94
	v_exp_f32_e32 v95, v95
	v_add_f32_e32 v189, v189, v88
	v_add_f32_e32 v183, v183, v89
	v_mfma_f32_32x32x16_bf16 v[0:15], v[228:231], v[80:83], v[0:15]
	v_add_f32_e32 v189, v189, v90
	v_add_f32_e32 v183, v183, v91
	v_add_f32_e32 v189, v189, v92
	v_add_f32_e32 v183, v183, v93
	v_add_f32_e32 v189, v189, v94
	v_add_f32_e32 v183, v183, v95
	v_cvt_pk_bf16_f32 v84, v88, v89
	v_cvt_pk_bf16_f32 v85, v90, v91
	v_cvt_pk_bf16_f32 v86, v92, v93
	v_cvt_pk_bf16_f32 v87, v94, v95
	s_nop 0
	s_waitcnt lgkmcnt(0)
	v_mfma_f32_32x32x16_bf16 v[48:63], v[232:235], v[84:87], v[48:63]
	v_mfma_f32_32x32x16_bf16 v[32:47], v[236:239], v[84:87], v[32:47]
	v_mfma_f32_32x32x16_bf16 v[16:31], v[240:243], v[84:87], v[16:31]
	v_mfma_f32_32x32x16_bf16 v[0:15], v[244:247], v[84:87], v[0:15]
	s_waitcnt vmcnt(0)
	s_barrier
	ds_read_b128 v[64:67], v173 offset:0
	ds_read_b128 v[68:71], v173 offset:4096
	s_add_u32 m0, s44, 0x6000
	ds_read_b128 v[72:75], v171 offset:0
	global_load_lds_dwordx4 v200, s[40:41]
	s_add_u32 m0, s44, 0x6400
	ds_read_b128 v[76:79], v171 offset:4096
	global_load_lds_dwordx4 v190, s[40:41]
	s_add_u32 m0, s45, 0x6000
	ds_read_b128 v[216:219], v169 offset:0
	global_load_lds_dwordx4 v192, s[42:43]
	s_add_u32 m0, s45, 0x6400
	ds_read_b128 v[220:223], v169 offset:4096
	global_load_lds_dwordx4 v194, s[42:43]
	s_add_u32 m0, s45, 0x6800
	ds_read_b128 v[224:227], v167 offset:0
	global_load_lds_dwordx4 v196, s[42:43]
	s_add_u32 m0, s45, 0x6c00
	ds_read_b128 v[228:231], v167 offset:4096
	global_load_lds_dwordx4 v198, s[42:43]
	ds_read_b128 v[232:235], v173 offset:8192
	ds_read_b128 v[236:239], v173 offset:12288
	ds_read_b128 v[240:243], v173 offset:16384
	ds_read_b128 v[244:247], v173 offset:20480
	s_add_u32 s40, s40, 0x18000
	s_addc_u32 s41, s41, 0
	s_add_u32 s42, s42, 0x80
	s_addc_u32 s43, s43, 0
	s_waitcnt lgkmcnt(11)
	v_mfma_f32_32x32x16_bf16 v[112:127], v[64:67], v[140:143], v[96:111]
	ds_read_b128 v[64:67], v171 offset:8192
	s_waitcnt lgkmcnt(11)
	v_mfma_f32_32x32x16_bf16 v[80:95], v[68:71], v[140:143], v[96:111]
	ds_read_b128 v[68:71], v171 offset:12288
	s_waitcnt lgkmcnt(11)
	v_mfma_f32_32x32x16_bf16 v[112:127], v[72:75], v[136:139], v[112:127]
	ds_read_b128 v[72:75], v171 offset:16384
	s_waitcnt lgkmcnt(11)
	v_mfma_f32_32x32x16_bf16 v[80:95], v[76:79], v[136:139], v[80:95]
	ds_read_b128 v[76:79], v171 offset:20480
	s_waitcnt lgkmcnt(11)
	v_mfma_f32_32x32x16_bf16 v[112:127], v[216:219], v[132:135], v[112:127]
	ds_read_b128 v[216:219], v169 offset:8192
	s_waitcnt lgkmcnt(11)
	v_mfma_f32_32x32x16_bf16 v[80:95], v[220:223], v[132:135], v[80:95]
	ds_read_b128 v[220:223], v169 offset:12288
	s_waitcnt lgkmcnt(11)
	v_mfma_f32_32x32x16_bf16 v[112:127], v[224:227], v[128:131], v[112:127]
	ds_read_b128 v[224:227], v169 offset:16384
	s_waitcnt lgkmcnt(11)
	v_mfma_f32_32x32x16_bf16 v[80:95], v[228:231], v[128:131], v[80:95]
	ds_read_b128 v[228:231], v169 offset:20480
	s_nop 7
	s_nop 3
	v_max3_f32 v175, v112, v113, v114
	v_max3_f32 v177, v115, v116, v117
	v_max3_f32 v179, v118, v119, v120
	v_max3_f32 v181, v121, v122, v123
	v_max3_f32 v248, v124, v125, v126
	v_max3_f32 v249, v127, v80, v81
	v_max3_f32 v250, v82, v83, v84
	v_max3_f32 v251, v85, v86, v87
	v_max3_f32 v253, v88, v89, v90
	v_max3_f32 v254, v91, v92, v93
	v_max3_f32 v175, v175, v177, v179
	v_max3_f32 v181, v181, v248, v249
	v_max3_f32 v250, v250, v251, v253
	v_max3_f32 v254, v254, v94, v95
	v_max3_f32 v175, v175, v181, v250
	v_max_f32_e32 v175, v175, v254
	v_cmp_lt_f32_e32 vcc, 0x41000000, v175
	s_cbranch_vccnz .Latt_resc_b
.Latt_cont_b:
	v_exp_f32_e32 v112, v112
	v_exp_f32_e32 v113, v113
	v_exp_f32_e32 v114, v114
	v_exp_f32_e32 v115, v115
	v_exp_f32_e32 v116, v116
	v_exp_f32_e32 v117, v117
	v_exp_f32_e32 v118, v118
	v_exp_f32_e32 v119, v119
	v_add_f32_e32 v189, v189, v112
	v_add_f32_e32 v183, v183, v113
	v_add_f32_e32 v189, v189, v114
	v_add_f32_e32 v183, v183, v115
	v_add_f32_e32 v189, v189, v116
	v_add_f32_e32 v183, v183, v117
	v_add_f32_e32 v189, v189, v118
	v_add_f32_e32 v183, v183, v119
	v_cvt_pk_bf16_f32 v112, v112, v113
	v_cvt_pk_bf16_f32 v113, v114, v115
	v_cvt_pk_bf16_f32 v114, v116, v117
	v_cvt_pk_bf16_f32 v115, v118, v119
	v_exp_f32_e32 v120, v120
	v_exp_f32_e32 v121, v121
	s_waitcnt lgkmcnt(8)
	v_mfma_f32_32x32x16_bf16 v[48:63], v[232:235], v[112:115], v[48:63]
	v_exp_f32_e32 v122, v122
	v_exp_f32_e32 v123, v123
	v_exp_f32_e32 v124, v124
	v_mfma_f32_32x32x16_bf16 v[32:47], v[236:239], v[112:115], v[32:47]
	v_exp_f32_e32 v125, v125
	v_exp_f32_e32 v126, v126
	v_exp_f32_e32 v127, v127
	v_mfma_f32_32x32x16_bf16 v[16:31], v[240:243], v[112:115], v[16:31]
	v_add_f32_e32 v189, v189, v120
	v_add_f32_e32 v183, v183, v121
	v_add_f32_e32 v189, v189, v122
	v_add_f32_e32 v183, v183, v123
	v_add_f32_e32 v189, v189, v124
	v_add_f32_e32 v183, v183, v125
	v_mfma_f32_32x32x16_bf16 v[0:15], v[244:247], v[112:115], v[0:15]
	ds_read_b128 v[232:235], v167 offset:8192
	ds_read_b128 v[236:239], v167 offset:12288
	ds_read_b128 v[240:243], v167 offset:16384
	ds_read_b128 v[244:247], v167 offset:20480
	v_add_f32_e32 v189, v189, v126
	v_add_f32_e32 v183, v183, v127
	v_cvt_pk_bf16_f32 v116, v120, v121
	v_cvt_pk_bf16_f32 v117, v122, v123
	v_cvt_pk_bf16_f32 v118, v124, v125
	v_cvt_pk_bf16_f32 v119, v126, v127
	s_nop 0
	s_waitcnt lgkmcnt(8)
	v_mfma_f32_32x32x16_bf16 v[48:63], v[64:67], v[116:119], v[48:63]
	v_exp_f32_e32 v80, v80
	v_exp_f32_e32 v81, v81
	v_exp_f32_e32 v82, v82
	v_mfma_f32_32x32x16_bf16 v[32:47], v[68:71], v[116:119], v[32:47]
	v_exp_f32_e32 v83, v83
	v_exp_f32_e32 v84, v84
	v_exp_f32_e32 v85, v85
	v_mfma_f32_32x32x16_bf16 v[16:31], v[72:75], v[116:119], v[16:31]
	v_exp_f32_e32 v86, v86
	v_exp_f32_e32 v87, v87
	v_add_f32_e32 v189, v189, v80
	v_add_f32_e32 v183, v183, v81
	v_mfma_f32_32x32x16_bf16 v[0:15], v[76:79], v[116:119], v[0:15]
	v_add_f32_e32 v189, v189, v82
	v_add_f32_e32 v183, v183, v83
	v_add_f32_e32 v189, v189, v84
	v_add_f32_e32 v183, v183, v85
	v_add_f32_e32 v189, v189, v86
	v_add_f32_e32 v183, v183, v87
	v_cvt_pk_bf16_f32 v80, v80, v81
	v_cvt_pk_bf16_f32 v81, v82, v83
	v_cvt_pk_bf16_f32 v82, v84, v85
	v_cvt_pk_bf16_f32 v83, v86, v87
	s_nop 0
	s_waitcnt lgkmcnt(4)
	v_mfma_f32_32x32x16_bf16 v[48:63], v[216:219], v[80:83], v[48:63]
	v_exp_f32_e32 v88, v88
	v_exp_f32_e32 v89, v89
	v_exp_f32_e32 v90, v90
	v_mfma_f32_32x32x16_bf16 v[32:47], v[220:223], v[80:83], v[32:47]
	v_exp_f32_e32 v91, v91
	v_exp_f32_e32 v92, v92
	v_exp_f32_e32 v93, v93
	v_mfma_f32_32x32x16_bf16 v[16:31], v[224:227], v[80:83], v[16:31]
	v_exp_f32_e32 v94, v94
	v_exp_f32_e32 v95, v95
	v_add_f32_e32 v189, v189, v88
	v_add_f32_e32 v183, v183, v89
	v_mfma_f32_32x32x16_bf16 v[0:15], v[228:231], v[80:83], v[0:15]
	v_add_f32_e32 v189, v189, v90
	v_add_f32_e32 v183, v183, v91
	v_add_f32_e32 v189, v189, v92
	v_add_f32_e32 v183, v183, v93
	v_add_f32_e32 v189, v189, v94
	v_add_f32_e32 v183, v183, v95
	v_cvt_pk_bf16_f32 v84, v88, v89
	v_cvt_pk_bf16_f32 v85, v90, v91
	v_cvt_pk_bf16_f32 v86, v92, v93
	v_cvt_pk_bf16_f32 v87, v94, v95
	s_nop 0
	s_waitcnt lgkmcnt(0)
	v_mfma_f32_32x32x16_bf16 v[48:63], v[232:235], v[84:87], v[48:63]
	v_mfma_f32_32x32x16_bf16 v[32:47], v[236:239], v[84:87], v[32:47]
	v_mfma_f32_32x32x16_bf16 v[16:31], v[240:243], v[84:87], v[16:31]
	v_mfma_f32_32x32x16_bf16 v[0:15], v[244:247], v[84:87], v[0:15]
	s_sub_u32 s46, s46, 1
	s_cmp_lg_u32 s46, 0
	s_cbranch_scc1 .Latt_loop
	v_mov_b64_e32 v[64:65], v[96:97]
	v_mov_b64_e32 v[66:67], v[98:99]
	v_mov_b64_e32 v[68:69], v[100:101]
	v_mov_b64_e32 v[70:71], v[102:103]
	v_mov_b64_e32 v[72:73], v[104:105]
	v_mov_b64_e32 v[74:75], v[106:107]
	v_mov_b64_e32 v[76:77], v[108:109]
	v_mov_b64_e32 v[78:79], v[110:111]
	v_add_f32_e32 v189, v189, v183
	v_mov_b32_e32 v248, v189
	s_nop 1
	v_permlane32_swap_b32_e32 v189, v248
	v_add_f32_e32 v189, v189, v248
	s_branch .LBB0_1482
.Latt_resc_a:
	v_mov_b32_e32 v177, v175
	s_nop 1
	v_permlane32_swap_b32_e32 v175, v177
	v_max_f32_e32 v175, v175, v177
	v_max_f32_e32 v248, 0, v175
	v_exp_f32_e64 v250, -v248
	v_sub_f32_e32 v112, v112, v248
	v_sub_f32_e32 v113, v113, v248
	v_sub_f32_e32 v114, v114, v248
	v_sub_f32_e32 v115, v115, v248
	v_sub_f32_e32 v116, v116, v248
	v_sub_f32_e32 v117, v117, v248
	v_sub_f32_e32 v118, v118, v248
	v_sub_f32_e32 v119, v119, v248
	v_sub_f32_e32 v120, v120, v248
	v_sub_f32_e32 v121, v121, v248
	v_sub_f32_e32 v122, v122, v248
	v_sub_f32_e32 v123, v123, v248
	v_sub_f32_e32 v124, v124, v248
	v_sub_f32_e32 v125, v125, v248
	v_sub_f32_e32 v126, v126, v248
	v_sub_f32_e32 v127, v127, v248
	v_sub_f32_e32 v80, v80, v248
	v_sub_f32_e32 v81, v81, v248
	v_sub_f32_e32 v82, v82, v248
	v_sub_f32_e32 v83, v83, v248
	v_sub_f32_e32 v84, v84, v248
	v_sub_f32_e32 v85, v85, v248
	v_sub_f32_e32 v86, v86, v248
	v_sub_f32_e32 v87, v87, v248
	v_sub_f32_e32 v88, v88, v248
	v_sub_f32_e32 v89, v89, v248
	v_sub_f32_e32 v90, v90, v248
	v_sub_f32_e32 v91, v91, v248
	v_sub_f32_e32 v92, v92, v248
	v_sub_f32_e32 v93, v93, v248
	v_sub_f32_e32 v94, v94, v248
	v_sub_f32_e32 v95, v95, v248
	v_add_f32_e32 v188, v188, v248
	v_mul_f32_e32 v189, v189, v250
	v_mul_f32_e32 v183, v183, v250
	v_pk_mul_f32 v[0:1], v[0:1], v[250:251] op_sel_hi:[1,0]
	v_pk_mul_f32 v[2:3], v[2:3], v[250:251] op_sel_hi:[1,0]
	v_pk_mul_f32 v[4:5], v[4:5], v[250:251] op_sel_hi:[1,0]
	v_pk_mul_f32 v[6:7], v[6:7], v[250:251] op_sel_hi:[1,0]
	v_pk_mul_f32 v[8:9], v[8:9], v[250:251] op_sel_hi:[1,0]
	v_pk_mul_f32 v[10:11], v[10:11], v[250:251] op_sel_hi:[1,0]
	v_pk_mul_f32 v[12:13], v[12:13], v[250:251] op_sel_hi:[1,0]
	v_pk_mul_f32 v[14:15], v[14:15], v[250:251] op_sel_hi:[1,0]
	v_pk_mul_f32 v[16:17], v[16:17], v[250:251] op_sel_hi:[1,0]
	v_pk_mul_f32 v[18:19], v[18:19], v[250:251] op_sel_hi:[1,0]
	v_pk_mul_f32 v[20:21], v[20:21], v[250:251] op_sel_hi:[1,0]
	v_pk_mul_f32 v[22:23], v[22:23], v[250:251] op_sel_hi:[1,0]
	v_pk_mul_f32 v[24:25], v[24:25], v[250:251] op_sel_hi:[1,0]
	v_pk_mul_f32 v[26:27], v[26:27], v[250:251] op_sel_hi:[1,0]
	v_pk_mul_f32 v[28:29], v[28:29], v[250:251] op_sel_hi:[1,0]
	v_pk_mul_f32 v[30:31], v[30:31], v[250:251] op_sel_hi:[1,0]
	v_pk_mul_f32 v[32:33], v[32:33], v[250:251] op_sel_hi:[1,0]
	v_pk_mul_f32 v[34:35], v[34:35], v[250:251] op_sel_hi:[1,0]
	v_pk_mul_f32 v[36:37], v[36:37], v[250:251] op_sel_hi:[1,0]
	v_pk_mul_f32 v[38:39], v[38:39], v[250:251] op_sel_hi:[1,0]
	v_pk_mul_f32 v[40:41], v[40:41], v[250:251] op_sel_hi:[1,0]
	v_pk_mul_f32 v[42:43], v[42:43], v[250:251] op_sel_hi:[1,0]
	v_pk_mul_f32 v[44:45], v[44:45], v[250:251] op_sel_hi:[1,0]
	v_pk_mul_f32 v[46:47], v[46:47], v[250:251] op_sel_hi:[1,0]
	v_pk_mul_f32 v[48:49], v[48:49], v[250:251] op_sel_hi:[1,0]
	v_pk_mul_f32 v[50:51], v[50:51], v[250:251] op_sel_hi:[1,0]
	v_pk_mul_f32 v[52:53], v[52:53], v[250:251] op_sel_hi:[1,0]
	v_pk_mul_f32 v[54:55], v[54:55], v[250:251] op_sel_hi:[1,0]
	v_pk_mul_f32 v[56:57], v[56:57], v[250:251] op_sel_hi:[1,0]
	v_pk_mul_f32 v[58:59], v[58:59], v[250:251] op_sel_hi:[1,0]
	v_pk_mul_f32 v[60:61], v[60:61], v[250:251] op_sel_hi:[1,0]
	v_pk_mul_f32 v[62:63], v[62:63], v[250:251] op_sel_hi:[1,0]
	v_sub_f32_e32 v96, 0, v188
	v_mov_b32_e32 v97, v96
	v_mov_b32_e32 v98, v96
	v_mov_b32_e32 v99, v96
	v_mov_b32_e32 v100, v96
	v_mov_b32_e32 v101, v96
	v_mov_b32_e32 v102, v96
	v_mov_b32_e32 v103, v96
	v_mov_b32_e32 v104, v96
	v_mov_b32_e32 v105, v96
	v_mov_b32_e32 v106, v96
	v_mov_b32_e32 v107, v96
	v_mov_b32_e32 v108, v96
	v_mov_b32_e32 v109, v96
	v_mov_b32_e32 v110, v96
	v_mov_b32_e32 v111, v96
	s_branch .Latt_cont_a
